# attn: next query's first tile gathered during the last P.V step (on v30)
# speedup vs baseline: 1.0107x; 1.0107x over previous
.LBB0_1397:
	s_or_b64 exec, exec, s[8:9]
	v_and_b32_e32 v14, 63, v0
	v_or_b32_e32 v12, 0x200, v0
	v_mul_u32_u24_e32 v11, 0x410, v11
	v_lshlrev_b32_e32 v58, 4, v14
	v_add3_u32 v68, 0, v11, v58
	v_lshrrev_b32_e32 v11, 6, v12
	v_and_b32_e32 v12, 0x1f8, v10
	v_lshrrev_b32_e32 v20, 1, v0
	v_and_b32_e32 v15, 15, v0
	s_movk_i32 s7, 0x410
	v_mul_u32_u24_e32 v11, 0x410, v11
	v_lshlrev_b32_e32 v12, 1, v12
	v_and_b32_e32 v20, 16, v20
	v_lshrrev_b32_e32 v21, 2, v0
	v_add3_u32 v69, 0, v11, v12
	v_mad_u32_u24 v11, v15, s7, 0
	v_and_b32_e32 v17, 48, v0
	v_and_or_b32 v20, v21, 4, v20
	v_lshlrev_b32_e32 v21, 9, v15
	v_add_u32_e32 v18, v11, v17
	v_sub_u32_e32 v11, v11, v21
	v_lshl_add_u64 v[12:13], s[66:67], 0, v[58:59]
	s_mov_b64 s[8:9], 0x18300000
	v_lshl_add_u32 v71, v20, 1, v11
	v_bfe_u32 v11, v0, 2, 2
	v_lshl_add_u64 v[62:63], v[12:13], 0, s[8:9]
	v_or_b32_e32 v11, v20, v11
	s_add_i32 s8, 0, 0x16a00
	s_add_i32 s9, 0, 0x1ee00
	v_mul_u32_u24_e32 v20, 0x420, v11
	v_and_b32_e32 v21, 24, v10
	s_and_b64 s[0:1], s[0:1], exec
	v_add3_u32 v22, s8, v20, v21
	s_cselect_b32 s8, 32, s84
	s_lshl_b32 s0, s12, 2
	s_ashr_i32 s1, s12, 2
	s_add_i32 s16, s0, 0
	s_and_b32 s0, s12, 3
	s_lshl_b32 s13, s1, 9
	s_cmp_gt_u32 s0, 1
	v_lshl_or_b32 v23, s0, 4, v15
	s_movk_i32 s7, 0x420
	v_add_u32_e32 v26, 0xffffe0, v23
	v_mov_b32_e32 v27, s9
	s_cselect_b64 vcc, -1, 0
	s_lshl_b32 s0, s1, 14
	v_bfe_u32 v16, v0, 4, 2
	v_mad_u32_u24 v11, v11, s7, 0
	v_mad_u32_u24 v24, v23, s7, 0
	v_mad_i32_i24 v26, v26, s7, v27
	s_add_i32 s7, s0, 0
	v_lshlrev_b32_e32 v12, 12, v16
	v_add_u32_e32 v25, 0xe600, v24
	s_cmp_lt_u32 s12, 4
	v_lshlrev_b32_e32 v23, 2, v23
	s_cselect_b64 s[0:1], -1, 0
	v_add3_u32 v76, s7, v12, v23
	v_cndmask_b32_e32 v12, v25, v26, vcc
	s_lshl_b32 s7, s12, 11
	v_mov_b32_e32 v27, 0xff800000
	s_lshl_b32 s18, s12, 1
	s_mul_i32 s20, s12, 0x420
	v_add_u32_e32 v75, 0, v23
	v_add_u32_e32 v23, s13, v12
	s_add_i32 s7, s7, 0
	v_lshlrev_b32_e32 v12, 2, v14
	v_add3_u32 v20, s9, v20, v21
	v_cndmask_b32_e64 v72, 0, v27, s[0:1]
	s_lshl_b32 s0, s12, 6
	s_add_i32 s21, s20, 0
	s_add_i32 s9, s9, s20
	v_add_u32_e32 v78, s7, v12
	s_or_b32 s7, s18, 1
	s_ashr_i32 s1, s0, 31
	s_add_i32 s22, s21, 0xe600
	v_add_u32_e32 v77, s9, v58
	s_lshl_b32 s9, s7, 10
	v_lshl_add_u32 v19, v14, 1, 0
	v_mul_u32_u24_e32 v13, 14, v14
	s_lshl_b32 s19, s12, 7
	v_add_u32_e32 v73, s21, v58
	v_add_u32_e32 v74, s22, v58
	s_add_i32 s9, s9, 0
	v_lshlrev_b32_e32 v58, 10, v15
	s_lshl_b64 s[0:1], s[0:1], 1
	v_add_u32_e32 v79, s9, v12
	v_add3_u32 v80, v11, v21, s19
	v_add3_u32 v11, v19, v13, s20
	v_lshl_add_u64 v[12:13], s[10:11], 0, v[58:59]
	v_lshlrev_b32_e32 v58, 3, v16
	s_add_u32 s0, s66, s0
	v_lshl_add_u64 v[12:13], v[12:13], 0, v[58:59]
	s_addc_u32 s1, s67, s1
	v_add_u32_e32 v24, s13, v24
	s_mulk_i32 s7, 0x210
	v_add_u32_e32 v82, 0xe600, v11
	v_lshl_add_u64 v[12:13], s[0:1], 0, v[12:13]
	s_mov_b64 s[0:1], 0x3cca0040
	s_ashr_i32 s9, s8, 31
	v_mov_b32_e32 v11, s16
	v_lshl_add_u32 v70, v0, 2, 0
	s_mov_b32 s17, 0xff800000
	v_add_u32_e32 v81, 0xe600, v80
	v_lshl_add_u64 v[64:65], v[12:13], 0, s[0:1]
	s_lshl_b64 s[0:1], s[8:9], 14
	v_add_u32_e32 v83, s13, v18
	v_add_u32_e32 v84, v24, v17
	v_add_u32_e32 v85, v23, v17
	s_movk_i32 s9, 0x7fff
	v_add_u32_e32 v86, s20, v19
	v_add_u32_e32 v87, s7, v19
	v_lshlrev_b32_e32 v66, 1, v10
	v_add_u32_e32 v88, s19, v22
	v_add_u32_e32 v89, s19, v20
	v_add_u32_e32 v90, 0xe000, v11
	v_add_u32_e32 v91, 0xe400, v11
	s_waitcnt vmcnt(0)
	s_mov_b32 s94, 1
	s_branch .LBB0_1400

.LBB0_1399:
	s_waitcnt lgkmcnt(0)
	s_barrier
	v_add_u32_e32 v67, 0xc000, v71
	ds_read_b64_tr_b16 v[12:13], v81 offset:8448
	ds_read_b64_tr_b16 v[10:11], v80 offset:58880
	ds_read2_b64 v[14:17], v67 offset0:80 offset1:82
	ds_read_b64_tr_b16 v[20:21], v81 offset:8480
	ds_read_b64_tr_b16 v[18:19], v80 offset:58912
	ds_read_b64_tr_b16 v[22:23], v80 offset:58944
	ds_read_b64_tr_b16 v[42:43], v80 offset:58976
	ds_read_b64_tr_b16 v[24:25], v81 offset:8512
	ds_read_b64_tr_b16 v[44:45], v81 offset:8544
	s_waitcnt lgkmcnt(6)
	v_mfma_f32_16x16x32_bf16 v[10:13], v[10:13], v[14:17], 0
	ds_read_b64_tr_b16 v[48:49], v88 offset:8448
	ds_read_b64_tr_b16 v[46:47], v88
	s_andn2_b64 vcc, exec, s[10:11]
	s_waitcnt lgkmcnt(6)
	v_mfma_f32_16x16x32_bf16 v[18:21], v[18:21], v[14:17], 0
	s_waitcnt lgkmcnt(3)
	v_mfma_f32_16x16x32_bf16 v[22:25], v[22:25], v[14:17], 0
	s_waitcnt lgkmcnt(2)
	v_mfma_f32_16x16x32_bf16 v[14:17], v[42:45], v[14:17], 0
	ds_read2_b64 v[42:45], v67 offset0:88 offset1:90
	ds_read_b64_tr_b16 v[50:51], v88 offset:32
	ds_read_b64_tr_b16 v[54:55], v88 offset:64
	ds_read_b64_tr_b16 v[92:93], v88 offset:96
	ds_read_b64_tr_b16 v[52:53], v88 offset:8480
	ds_read_b64_tr_b16 v[56:57], v88 offset:8512
	ds_read_b64_tr_b16 v[94:95], v88 offset:8544
	s_waitcnt lgkmcnt(0)
	s_barrier
	s_waitcnt vmcnt(3)
	ds_write_b128 v82, v[26:29]
	s_waitcnt vmcnt(2)
	ds_write_b128 v82, v[30:33] offset:8448
	s_waitcnt vmcnt(1)
	ds_write_b128 v82, v[34:37] offset:16896
	s_waitcnt vmcnt(0)
	ds_write_b128 v82, v[38:41] offset:25344
	v_mov_b32_e32 v26, s16
	v_add_u32_e32 v112, 0xe000, v26
	ds_read2_b32 v[26:27], v112 offset0:192 offset1:200
	ds_read2_b32 v[36:37], v112 offset0:208 offset1:216
	s_waitcnt lgkmcnt(12)
	v_mfma_f32_16x16x32_bf16 v[10:13], v[46:49], v[42:45], v[10:13]
	s_waitcnt lgkmcnt(1)
	v_max_i32_e32 v58, 0, v26
	v_lshlrev_b64 v[28:29], 10, v[58:59]
	v_max_i32_e32 v58, 0, v27
	v_lshl_add_u64 v[34:35], v[62:63], 0, v[28:29]
	v_lshlrev_b64 v[26:27], 10, v[58:59]
	s_waitcnt lgkmcnt(0)
	v_max_i32_e32 v58, 0, v36
	v_lshl_add_u64 v[38:39], v[62:63], 0, v[26:27]
	global_load_dwordx4 v[26:29], v[34:35], off
	global_load_dwordx4 v[30:33], v[38:39], off
	v_lshlrev_b64 v[34:35], 10, v[58:59]
	v_max_i32_e32 v58, 0, v37
	ds_read2_b32 v[48:49], v112 offset0:224 offset1:232
	v_lshl_add_u64 v[46:47], v[62:63], 0, v[34:35]
	v_lshlrev_b64 v[34:35], 10, v[58:59]
	v_mfma_f32_16x16x32_bf16 v[18:21], v[50:53], v[42:45], v[18:21]
	v_lshl_add_u64 v[50:51], v[62:63], 0, v[34:35]
	global_load_dwordx4 v[34:37], v[46:47], off
	global_load_dwordx4 v[38:41], v[50:51], off
	ds_read2_b32 v[98:99], v112 offset0:240 offset1:248
	s_waitcnt lgkmcnt(1)
	v_max_i32_e32 v58, 0, v48
	v_lshlrev_b64 v[46:47], 10, v[58:59]
	v_max_i32_e32 v58, 0, v49
	v_lshl_add_u64 v[96:97], v[62:63], 0, v[46:47]
	v_lshlrev_b64 v[46:47], 10, v[58:59]
	s_waitcnt lgkmcnt(0)
	v_max_i32_e32 v58, 0, v98
	v_lshl_add_u64 v[100:101], v[62:63], 0, v[46:47]
	global_load_dwordx4 v[46:49], v[96:97], off
	global_load_dwordx4 v[50:53], v[100:101], off
	v_lshlrev_b64 v[96:97], 10, v[58:59]
	v_max_i32_e32 v58, 0, v99
	v_lshl_add_u64 v[104:105], v[62:63], 0, v[96:97]
	v_lshlrev_b64 v[96:97], 10, v[58:59]
	v_lshl_add_u64 v[106:107], v[62:63], 0, v[96:97]
	global_load_dwordx4 v[96:99], v[104:105], off
	global_load_dwordx4 v[100:103], v[106:107], off
	s_waitcnt lgkmcnt(0)
	s_barrier
	v_mfma_f32_16x16x32_bf16 v[22:25], v[54:57], v[42:45], v[22:25]
	ds_read_b64_tr_b16 v[56:57], v81 offset:8448
	ds_read_b64_tr_b16 v[54:55], v80 offset:58880
	v_mfma_f32_16x16x32_bf16 v[14:17], v[92:95], v[42:45], v[14:17]
	ds_read2_b64 v[42:45], v67 offset0:64 offset1:66
	ds_read_b64_tr_b16 v[94:95], v81 offset:8480
	ds_read_b64_tr_b16 v[92:93], v80 offset:58912
	ds_read_b64_tr_b16 v[104:105], v80 offset:58944
	ds_read_b64_tr_b16 v[108:109], v80 offset:58976
	ds_read_b64_tr_b16 v[106:107], v81 offset:8512
	ds_read_b64_tr_b16 v[110:111], v81 offset:8544
	s_waitcnt lgkmcnt(6)
	v_mfma_f32_16x16x32_bf16 v[10:13], v[54:57], v[42:45], v[10:13]
	ds_read_b64_tr_b16 v[56:57], v89 offset:8448
	ds_read_b64_tr_b16 v[54:55], v89
	s_waitcnt lgkmcnt(6)
	v_mfma_f32_16x16x32_bf16 v[18:21], v[92:95], v[42:45], v[18:21]
	s_waitcnt lgkmcnt(3)
	v_mfma_f32_16x16x32_bf16 v[22:25], v[104:107], v[42:45], v[22:25]
	s_waitcnt lgkmcnt(2)
	v_mfma_f32_16x16x32_bf16 v[14:17], v[108:111], v[42:45], v[14:17]
	ds_read2_b64 v[42:45], v67 offset0:72 offset1:74
	ds_read_b64_tr_b16 v[92:93], v89 offset:32
	ds_read_b64_tr_b16 v[104:105], v89 offset:64
	ds_read_b64_tr_b16 v[108:109], v89 offset:96
	ds_read_b64_tr_b16 v[94:95], v89 offset:8480
	ds_read_b64_tr_b16 v[106:107], v89 offset:8512
	ds_read_b64_tr_b16 v[110:111], v89 offset:8544
	s_waitcnt lgkmcnt(0)
	s_barrier
	s_waitcnt lgkmcnt(6)
	v_mfma_f32_16x16x32_bf16 v[10:13], v[54:57], v[42:45], v[10:13]
	s_waitcnt vmcnt(7)
	ds_write_b128 v82, v[26:29]
	s_waitcnt vmcnt(6)
	ds_write_b128 v82, v[30:33] offset:8448
	s_waitcnt vmcnt(5)
	ds_write_b128 v82, v[34:37] offset:16896
	s_waitcnt vmcnt(4)
	ds_write_b128 v82, v[38:41] offset:25344
	s_waitcnt vmcnt(3)
	ds_write_b128 v82, v[46:49] offset:33792
	s_waitcnt vmcnt(2)
	ds_write_b128 v82, v[50:53] offset:42240
	s_waitcnt vmcnt(1)
	ds_write_b128 v82, v[96:99] offset:50688
	s_waitcnt vmcnt(0)
	ds_write_b128 v82, v[100:103] offset:59136
	ds_read2_b32 v[26:27], v112 offset0:128 offset1:136
	ds_read2_b32 v[36:37], v112 offset0:144 offset1:152
	s_waitcnt lgkmcnt(12)
	v_mfma_f32_16x16x32_bf16 v[18:21], v[92:95], v[42:45], v[18:21]
	s_waitcnt lgkmcnt(1)
	v_max_i32_e32 v58, 0, v26
	v_lshlrev_b64 v[28:29], 10, v[58:59]
	v_max_i32_e32 v58, 0, v27
	v_lshl_add_u64 v[34:35], v[62:63], 0, v[28:29]
	v_lshlrev_b64 v[26:27], 10, v[58:59]
	s_waitcnt lgkmcnt(0)
	v_max_i32_e32 v58, 0, v36
	v_lshl_add_u64 v[38:39], v[62:63], 0, v[26:27]
	global_load_dwordx4 v[26:29], v[34:35], off
	global_load_dwordx4 v[30:33], v[38:39], off
	v_lshlrev_b64 v[34:35], 10, v[58:59]
	v_max_i32_e32 v58, 0, v37
	ds_read2_b32 v[48:49], v112 offset0:160 offset1:168
	v_lshl_add_u64 v[46:47], v[62:63], 0, v[34:35]
	v_lshlrev_b64 v[34:35], 10, v[58:59]
	v_lshl_add_u64 v[50:51], v[62:63], 0, v[34:35]
	global_load_dwordx4 v[34:37], v[46:47], off
	global_load_dwordx4 v[38:41], v[50:51], off
	ds_read2_b32 v[56:57], v112 offset0:176 offset1:184
	s_waitcnt lgkmcnt(1)
	v_max_i32_e32 v58, 0, v48
	v_lshlrev_b64 v[46:47], 10, v[58:59]
	v_max_i32_e32 v58, 0, v49
	v_lshl_add_u64 v[54:55], v[62:63], 0, v[46:47]
	v_lshlrev_b64 v[46:47], 10, v[58:59]
	s_waitcnt lgkmcnt(0)
	v_max_i32_e32 v58, 0, v56
	v_lshl_add_u64 v[92:93], v[62:63], 0, v[46:47]
	global_load_dwordx4 v[46:49], v[54:55], off
	global_load_dwordx4 v[50:53], v[92:93], off
	v_lshlrev_b64 v[54:55], 10, v[58:59]
	v_max_i32_e32 v58, 0, v57
	v_lshl_add_u64 v[96:97], v[62:63], 0, v[54:55]
	v_lshlrev_b64 v[54:55], 10, v[58:59]
	v_lshl_add_u64 v[98:99], v[62:63], 0, v[54:55]
	global_load_dwordx4 v[54:57], v[96:97], off
	global_load_dwordx4 v[92:95], v[98:99], off
	s_waitcnt lgkmcnt(0)
	s_barrier
	ds_read_b64_tr_b16 v[98:99], v81 offset:8448
	ds_read_b64_tr_b16 v[96:97], v80 offset:58880
	v_mfma_f32_16x16x32_bf16 v[22:25], v[104:107], v[42:45], v[22:25]
	v_mfma_f32_16x16x32_bf16 v[14:17], v[108:111], v[42:45], v[14:17]
	ds_read2_b64 v[42:45], v67 offset0:48 offset1:50
	ds_read_b64_tr_b16 v[102:103], v81 offset:8480
	ds_read_b64_tr_b16 v[100:101], v80 offset:58912
	ds_read_b64_tr_b16 v[104:105], v80 offset:58944
	ds_read_b64_tr_b16 v[108:109], v80 offset:58976
	ds_read_b64_tr_b16 v[106:107], v81 offset:8512
	ds_read_b64_tr_b16 v[110:111], v81 offset:8544
	s_waitcnt lgkmcnt(6)
	v_mfma_f32_16x16x32_bf16 v[10:13], v[96:99], v[42:45], v[10:13]
	ds_read_b64_tr_b16 v[98:99], v88 offset:8448
	s_waitcnt lgkmcnt(5)
	v_mfma_f32_16x16x32_bf16 v[18:21], v[100:103], v[42:45], v[18:21]
	s_waitcnt lgkmcnt(2)
	v_mfma_f32_16x16x32_bf16 v[22:25], v[104:107], v[42:45], v[22:25]
	ds_read_b64_tr_b16 v[96:97], v88
	ds_read2_b64 v[100:103], v67 offset0:56 offset1:58
	ds_read_b64_tr_b16 v[106:107], v88 offset:8480
	s_waitcnt lgkmcnt(4)
	v_mfma_f32_16x16x32_bf16 v[14:17], v[108:111], v[42:45], v[14:17]
	ds_read_b64_tr_b16 v[104:105], v88 offset:32
	ds_read_b64_tr_b16 v[42:43], v88 offset:64
	ds_read_b64_tr_b16 v[108:109], v88 offset:96
	ds_read_b64_tr_b16 v[44:45], v88 offset:8512
	ds_read_b64_tr_b16 v[110:111], v88 offset:8544
	s_waitcnt lgkmcnt(0)
	s_barrier
	s_waitcnt vmcnt(7)
	ds_write_b128 v82, v[26:29]
	s_waitcnt vmcnt(6)
	ds_write_b128 v82, v[30:33] offset:8448
	s_waitcnt vmcnt(5)
	ds_write_b128 v82, v[34:37] offset:16896
	s_waitcnt vmcnt(4)
	ds_write_b128 v82, v[38:41] offset:25344
	s_waitcnt vmcnt(3)
	ds_write_b128 v82, v[46:49] offset:33792
	s_waitcnt vmcnt(2)
	ds_write_b128 v82, v[50:53] offset:42240
	s_waitcnt vmcnt(1)
	ds_write_b128 v82, v[54:57] offset:50688
	s_waitcnt vmcnt(0)
	ds_write_b128 v82, v[92:95] offset:59136
	s_mov_b64 s[96:97], exec
	s_mov_b64 exec, s[4:5]
	ds_write_b32 v70, v1 offset:57856
	s_mov_b64 exec, s[96:97]
	s_waitcnt lgkmcnt(0)
	s_barrier
	ds_read2_b32 v[224:225], v90 offset0:128 offset1:136
	ds_read2_b32 v[226:227], v90 offset0:144 offset1:152
	ds_read2_b32 v[228:229], v90 offset0:160 offset1:168
	ds_read2_b32 v[230:231], v90 offset0:176 offset1:184
	v_mov_b32_e32 v241, 0
	s_waitcnt lgkmcnt(3)
	v_max_i32_e32 v240, 0, v224
	v_lshlrev_b64 v[242:243], 10, v[240:241]
	v_lshl_add_u64 v[242:243], v[62:63], 0, v[242:243]
	global_load_dwordx4 v[152:155], v[242:243], off
	v_max_i32_e32 v240, 0, v225
	v_lshlrev_b64 v[244:245], 10, v[240:241]
	v_lshl_add_u64 v[244:245], v[62:63], 0, v[244:245]
	global_load_dwordx4 v[156:159], v[244:245], off
	s_waitcnt lgkmcnt(2)
	v_max_i32_e32 v240, 0, v226
	v_lshlrev_b64 v[246:247], 10, v[240:241]
	v_lshl_add_u64 v[246:247], v[62:63], 0, v[246:247]
	global_load_dwordx4 v[160:163], v[246:247], off
	v_max_i32_e32 v240, 0, v227
	v_lshlrev_b64 v[248:249], 10, v[240:241]
	v_lshl_add_u64 v[248:249], v[62:63], 0, v[248:249]
	global_load_dwordx4 v[164:167], v[248:249], off
	s_waitcnt lgkmcnt(1)
	v_max_i32_e32 v240, 0, v228
	v_lshlrev_b64 v[242:243], 10, v[240:241]
	v_lshl_add_u64 v[242:243], v[62:63], 0, v[242:243]
	global_load_dwordx4 v[168:171], v[242:243], off
	v_max_i32_e32 v240, 0, v229
	v_lshlrev_b64 v[244:245], 10, v[240:241]
	v_lshl_add_u64 v[244:245], v[62:63], 0, v[244:245]
	global_load_dwordx4 v[172:175], v[244:245], off
	s_waitcnt lgkmcnt(0)
	v_max_i32_e32 v240, 0, v230
	v_lshlrev_b64 v[246:247], 10, v[240:241]
	v_lshl_add_u64 v[246:247], v[62:63], 0, v[246:247]
	global_load_dwordx4 v[176:179], v[246:247], off
	v_max_i32_e32 v240, 0, v231
	v_lshlrev_b64 v[248:249], 10, v[240:241]
	v_lshl_add_u64 v[248:249], v[62:63], 0, v[248:249]
	global_load_dwordx4 v[180:183], v[248:249], off
	ds_read_b64_tr_b16 v[28:29], v81 offset:8448
	ds_read_b64_tr_b16 v[26:27], v80 offset:58880
	s_waitcnt lgkmcnt(14)
	v_mfma_f32_16x16x32_bf16 v[10:13], v[96:99], v[100:103], v[10:13]
	v_mfma_f32_16x16x32_bf16 v[18:21], v[104:107], v[100:103], v[18:21]
	s_waitcnt lgkmcnt(11)
	v_mfma_f32_16x16x32_bf16 v[22:25], v[42:45], v[100:103], v[22:25]
	ds_read2_b64 v[30:33], v67 offset0:32 offset1:34
	ds_read_b64_tr_b16 v[36:37], v81 offset:8480
	ds_read_b64_tr_b16 v[34:35], v80 offset:58912
	ds_read_b64_tr_b16 v[38:39], v80 offset:58944
	ds_read_b64_tr_b16 v[42:43], v80 offset:58976
	ds_read_b64_tr_b16 v[40:41], v81 offset:8512
	ds_read_b64_tr_b16 v[44:45], v81 offset:8544
	s_waitcnt lgkmcnt(14)
	v_mfma_f32_16x16x32_bf16 v[14:17], v[108:111], v[100:103], v[14:17]
	s_waitcnt lgkmcnt(6)
	v_mfma_f32_16x16x32_bf16 v[10:13], v[26:29], v[30:33], v[10:13]
	ds_read_b64_tr_b16 v[28:29], v88 offset:8448
	ds_read_b64_tr_b16 v[26:27], v88
	s_waitcnt lgkmcnt(6)
	v_mfma_f32_16x16x32_bf16 v[18:21], v[34:37], v[30:33], v[18:21]
	s_waitcnt lgkmcnt(3)
	v_mfma_f32_16x16x32_bf16 v[22:25], v[38:41], v[30:33], v[22:25]
	s_waitcnt lgkmcnt(2)
	v_mfma_f32_16x16x32_bf16 v[14:17], v[42:45], v[30:33], v[14:17]
	ds_read2_b64 v[30:33], v67 offset0:40 offset1:42
	ds_read_b64_tr_b16 v[36:37], v88 offset:8480
	ds_read_b64_tr_b16 v[34:35], v88 offset:32
	ds_read_b64_tr_b16 v[38:39], v88 offset:64
	ds_read_b64_tr_b16 v[42:43], v88 offset:96
	ds_read_b64_tr_b16 v[40:41], v88 offset:8512
	ds_read_b64_tr_b16 v[44:45], v88 offset:8544
	s_waitcnt lgkmcnt(6)
	v_mfma_f32_16x16x32_bf16 v[10:13], v[26:29], v[30:33], v[10:13]
	s_waitcnt lgkmcnt(4)
	v_mfma_f32_16x16x32_bf16 v[18:21], v[34:37], v[30:33], v[18:21]
	s_waitcnt lgkmcnt(1)
	v_mfma_f32_16x16x32_bf16 v[22:25], v[38:41], v[30:33], v[22:25]
	s_nop 3
	v_cvt_pk_bf16_f32 v10, v10, v11
	v_cvt_pk_bf16_f32 v11, v12, v13
	global_store_dwordx2 v[64:65], v[10:11], off offset:-64
	s_waitcnt lgkmcnt(0)
	v_mfma_f32_16x16x32_bf16 v[14:17], v[42:45], v[30:33], v[14:17]
	v_cvt_pk_bf16_f32 v10, v18, v19
	v_cvt_pk_bf16_f32 v11, v20, v21
	global_store_dwordx2 v[64:65], v[10:11], off offset:-32
	v_cvt_pk_bf16_f32 v10, v22, v23
	v_cvt_pk_bf16_f32 v11, v24, v25
	global_store_dwordx2 v[64:65], v[10:11], off
	s_nop 1
	v_cvt_pk_bf16_f32 v10, v14, v15
	v_cvt_pk_bf16_f32 v11, v16, v17
	global_store_dwordx2 v[64:65], v[10:11], off offset:32
	v_lshl_add_u64 v[64:65], v[64:65], 0, s[0:1]
	s_cbranch_vccz .LBB0_1405
.LBB0_1400:
	s_waitcnt lgkmcnt(0)
	s_barrier
	ds_write_b128 v68, v[2:5]
	ds_write_b128 v69, v[6:9]
	s_cmp_eq_u32 s94, 0
	s_cbranch_scc1 .Lat_sl_skip
	s_and_saveexec_b64 s[10:11], s[4:5]
	ds_write_b32 v70, v1 offset:57856
	s_or_b64 exec, exec, s[10:11]
.Lat_sl_skip:
	s_waitcnt lgkmcnt(0)
	s_barrier
	s_cmp_eq_u32 s94, 0
	s_cbranch_scc1 .Lat_g0_skip
	s_mov_b32 s94, 0
	ds_read2_b32 v[224:225], v90 offset0:128 offset1:136
	ds_read2_b32 v[226:227], v90 offset0:144 offset1:152
	ds_read2_b32 v[228:229], v90 offset0:160 offset1:168
	ds_read2_b32 v[230:231], v90 offset0:176 offset1:184
	v_mov_b32_e32 v241, 0
	s_waitcnt lgkmcnt(3)
	v_max_i32_e32 v240, 0, v224
	v_lshlrev_b64 v[242:243], 10, v[240:241]
	v_lshl_add_u64 v[242:243], v[62:63], 0, v[242:243]
	global_load_dwordx4 v[152:155], v[242:243], off
	v_max_i32_e32 v240, 0, v225
	v_lshlrev_b64 v[244:245], 10, v[240:241]
	v_lshl_add_u64 v[244:245], v[62:63], 0, v[244:245]
	global_load_dwordx4 v[156:159], v[244:245], off
	s_waitcnt lgkmcnt(2)
	v_max_i32_e32 v240, 0, v226
	v_lshlrev_b64 v[246:247], 10, v[240:241]
	v_lshl_add_u64 v[246:247], v[62:63], 0, v[246:247]
	global_load_dwordx4 v[160:163], v[246:247], off
	v_max_i32_e32 v240, 0, v227
	v_lshlrev_b64 v[248:249], 10, v[240:241]
	v_lshl_add_u64 v[248:249], v[62:63], 0, v[248:249]
	global_load_dwordx4 v[164:167], v[248:249], off
	s_waitcnt lgkmcnt(1)
	v_max_i32_e32 v240, 0, v228
	v_lshlrev_b64 v[242:243], 10, v[240:241]
	v_lshl_add_u64 v[242:243], v[62:63], 0, v[242:243]
	global_load_dwordx4 v[168:171], v[242:243], off
	v_max_i32_e32 v240, 0, v229
	v_lshlrev_b64 v[244:245], 10, v[240:241]
	v_lshl_add_u64 v[244:245], v[62:63], 0, v[244:245]
	global_load_dwordx4 v[172:175], v[244:245], off
	s_waitcnt lgkmcnt(0)
	v_max_i32_e32 v240, 0, v230
	v_lshlrev_b64 v[246:247], 10, v[240:241]
	v_lshl_add_u64 v[246:247], v[62:63], 0, v[246:247]
	global_load_dwordx4 v[176:179], v[246:247], off
	v_max_i32_e32 v240, 0, v231
	v_lshlrev_b64 v[248:249], 10, v[240:241]
	v_lshl_add_u64 v[248:249], v[62:63], 0, v[248:249]
	global_load_dwordx4 v[180:183], v[248:249], off
	s_waitcnt vmcnt(0)
.Lat_g0_skip:
	s_add_i32 s6, s6, s8
	s_cmp_ge_i32 s6, s3
	s_waitcnt lgkmcnt(1)
	s_waitcnt lgkmcnt(0)
	s_waitcnt lgkmcnt(0)
	s_waitcnt lgkmcnt(0)
	ds_read_b128 v[54:57], v83
	ds_read_b128 v[46:49], v83 offset:64
	ds_read_b128 v[50:53], v83 offset:128
	ds_read_b128 v[42:45], v83 offset:192
	ds_read_b128 v[22:25], v83 offset:256
	ds_read_b128 v[18:21], v83 offset:320
	ds_read_b128 v[14:17], v83 offset:384
	ds_read_b128 v[10:13], v83 offset:448
	s_waitcnt lgkmcnt(0)
	s_barrier
	s_waitcnt vmcnt(11)
	ds_write_b128 v73, v[152:155] offset:58880
	s_waitcnt vmcnt(10)
	ds_write_b128 v74, v[156:159] offset:8448
	s_waitcnt vmcnt(9)
	ds_write_b128 v74, v[160:163] offset:16896
	s_waitcnt vmcnt(8)
	ds_write_b128 v74, v[164:167] offset:25344
	s_waitcnt vmcnt(7)
	ds_write_b128 v74, v[168:171] offset:33792
	s_waitcnt vmcnt(6)
	ds_write_b128 v74, v[172:175] offset:42240
	s_waitcnt vmcnt(5)
	ds_write_b128 v74, v[176:179] offset:50688
	s_waitcnt vmcnt(4)
	ds_write_b128 v74, v[180:183] offset:59136
	ds_read2_b32 v[26:27], v90 offset0:192 offset1:200
	ds_read2_b32 v[28:29], v90 offset0:208 offset1:216
	ds_read2_b32 v[34:35], v90 offset0:224 offset1:232
	ds_read2_b32 v[92:93], v90 offset0:240 offset1:248
	s_waitcnt lgkmcnt(3)
	v_max_i32_e32 v58, 0, v26
	v_lshlrev_b64 v[30:31], 10, v[58:59]
	v_max_i32_e32 v58, 0, v27
	v_lshlrev_b64 v[26:27], 10, v[58:59]
	s_waitcnt lgkmcnt(2)
	v_max_i32_e32 v58, 0, v28
	v_lshl_add_u64 v[36:37], v[62:63], 0, v[30:31]
	v_lshlrev_b64 v[40:41], 10, v[58:59]
	v_max_i32_e32 v58, 0, v29
	v_lshl_add_u64 v[38:39], v[62:63], 0, v[26:27]
	global_load_dwordx4 v[26:29], v[36:37], off
	global_load_dwordx4 v[30:33], v[38:39], off
	v_lshlrev_b64 v[36:37], 10, v[58:59]
	s_waitcnt lgkmcnt(1)
	v_max_i32_e32 v58, 0, v34
	v_lshl_add_u64 v[94:95], v[62:63], 0, v[40:41]
	v_lshlrev_b64 v[98:99], 10, v[58:59]
	v_max_i32_e32 v58, 0, v35
	v_lshl_add_u64 v[96:97], v[62:63], 0, v[36:37]
	global_load_dwordx4 v[34:37], v[94:95], off
	global_load_dwordx4 v[38:41], v[96:97], off
	v_lshlrev_b64 v[94:95], 10, v[58:59]
	s_waitcnt lgkmcnt(0)
	v_max_i32_e32 v58, 0, v92
	v_lshl_add_u64 v[100:101], v[62:63], 0, v[98:99]
	v_lshlrev_b64 v[104:105], 10, v[58:59]
	v_max_i32_e32 v58, 0, v93
	v_lshl_add_u64 v[102:103], v[62:63], 0, v[94:95]
	global_load_dwordx4 v[92:95], v[100:101], off
	global_load_dwordx4 v[96:99], v[102:103], off
	v_lshl_add_u64 v[108:109], v[62:63], 0, v[104:105]
	v_lshlrev_b64 v[100:101], 10, v[58:59]
	v_lshl_add_u64 v[110:111], v[62:63], 0, v[100:101]
	global_load_dwordx4 v[100:103], v[108:109], off
	global_load_dwordx4 v[104:107], v[110:111], off
	s_waitcnt lgkmcnt(0)
	s_barrier
	ds_read_b128 v[108:111], v84 offset:58880
	ds_read_b32 v58, v75 offset:57856
	s_waitcnt lgkmcnt(1)
	v_mfma_f32_16x16x32_bf16 v[108:111], v[54:57], v[108:111], 0
	ds_read_b128 v[112:115], v84 offset:58944
	ds_read_b128 v[116:119], v84 offset:59008
	s_waitcnt lgkmcnt(2)
	v_cmp_gt_i32_e32 vcc, 0, v58
	s_waitcnt lgkmcnt(1)
	v_mfma_f32_16x16x32_bf16 v[108:111], v[46:49], v[112:115], v[108:111]
	s_waitcnt lgkmcnt(0)
	v_mfma_f32_16x16x32_bf16 v[108:111], v[50:53], v[116:119], v[108:111]
	ds_read_b128 v[112:115], v84 offset:59072
	ds_read_b128 v[116:119], v84 offset:59136
	s_waitcnt lgkmcnt(1)
	v_mfma_f32_16x16x32_bf16 v[108:111], v[42:45], v[112:115], v[108:111]
	s_waitcnt lgkmcnt(0)
	v_mfma_f32_16x16x32_bf16 v[108:111], v[22:25], v[116:119], v[108:111]
	ds_read_b128 v[112:115], v84 offset:59200
	ds_read_b128 v[116:119], v84 offset:59264
	s_waitcnt lgkmcnt(1)
	v_mfma_f32_16x16x32_bf16 v[108:111], v[18:21], v[112:115], v[108:111]
	ds_read_b128 v[112:115], v84 offset:59328
	s_waitcnt lgkmcnt(1)
	v_mfma_f32_16x16x32_bf16 v[108:111], v[14:17], v[116:119], v[108:111]
	s_waitcnt lgkmcnt(0)
	v_mfma_f32_16x16x32_bf16 v[108:111], v[10:13], v[112:115], v[108:111]
	s_nop 7
	v_mul_f32_e32 v67, 0x3db504f3, v108
	v_mul_f32_e32 v108, 0x3db504f3, v109
	v_mul_f32_e32 v109, 0x3db504f3, v110
	v_mul_f32_e32 v110, 0x3db504f3, v111
	v_cndmask_b32_e32 v58, v67, v72, vcc
	v_cndmask_b32_e32 v67, v108, v72, vcc
	v_cndmask_b32_e32 v108, v109, v72, vcc
	v_cndmask_b32_e32 v109, v110, v72, vcc
	ds_write2st64_b32 v76, v58, v67 offset0:65 offset1:69
	ds_write2st64_b32 v76, v108, v109 offset0:73 offset1:77
	s_waitcnt lgkmcnt(0)
	s_barrier
	s_waitcnt vmcnt(7)
	ds_write_b128 v73, v[26:29] offset:58880
	s_waitcnt vmcnt(6)
	ds_write_b128 v74, v[30:33] offset:8448
	s_waitcnt vmcnt(5)
	ds_write_b128 v74, v[34:37] offset:16896
	s_waitcnt vmcnt(4)
	ds_write_b128 v74, v[38:41] offset:25344
	s_waitcnt vmcnt(3)
	ds_write_b128 v74, v[92:95] offset:33792
	s_waitcnt vmcnt(2)
	ds_write_b128 v74, v[96:99] offset:42240
	s_waitcnt vmcnt(1)
	ds_write_b128 v74, v[100:103] offset:50688
	s_waitcnt vmcnt(0)
	ds_write_b128 v74, v[104:107] offset:59136
	ds_read2_b32 v[26:27], v91 offset1:8
	ds_read2_b32 v[28:29], v91 offset0:16 offset1:24
	ds_read2_b32 v[34:35], v91 offset0:32 offset1:40
	ds_read2_b32 v[92:93], v91 offset0:48 offset1:56
	s_waitcnt lgkmcnt(3)
	v_max_i32_e32 v58, 0, v26
	v_lshlrev_b64 v[30:31], 10, v[58:59]
	v_max_i32_e32 v58, 0, v27
	v_lshlrev_b64 v[26:27], 10, v[58:59]
	s_waitcnt lgkmcnt(2)
	v_max_i32_e32 v58, 0, v28
	v_lshl_add_u64 v[36:37], v[62:63], 0, v[30:31]
	v_lshlrev_b64 v[40:41], 10, v[58:59]
	v_max_i32_e32 v58, 0, v29
	v_lshl_add_u64 v[38:39], v[62:63], 0, v[26:27]
	global_load_dwordx4 v[26:29], v[36:37], off
	global_load_dwordx4 v[30:33], v[38:39], off
	v_lshlrev_b64 v[36:37], 10, v[58:59]
	s_waitcnt lgkmcnt(1)
	v_max_i32_e32 v58, 0, v34
	v_lshl_add_u64 v[94:95], v[62:63], 0, v[40:41]
	v_lshlrev_b64 v[98:99], 10, v[58:59]
	v_max_i32_e32 v58, 0, v35
	v_lshl_add_u64 v[96:97], v[62:63], 0, v[36:37]
	global_load_dwordx4 v[34:37], v[94:95], off
	global_load_dwordx4 v[38:41], v[96:97], off
	v_lshlrev_b64 v[94:95], 10, v[58:59]
	s_waitcnt lgkmcnt(0)
	v_max_i32_e32 v58, 0, v92
	v_lshl_add_u64 v[100:101], v[62:63], 0, v[98:99]
	v_lshlrev_b64 v[104:105], 10, v[58:59]
	v_max_i32_e32 v58, 0, v93
	v_lshl_add_u64 v[102:103], v[62:63], 0, v[94:95]
	global_load_dwordx4 v[92:95], v[100:101], off
	global_load_dwordx4 v[96:99], v[102:103], off
	v_lshl_add_u64 v[108:109], v[62:63], 0, v[104:105]
	v_lshlrev_b64 v[100:101], 10, v[58:59]
	v_lshl_add_u64 v[110:111], v[62:63], 0, v[100:101]
	global_load_dwordx4 v[100:103], v[108:109], off
	global_load_dwordx4 v[104:107], v[110:111], off
	s_waitcnt lgkmcnt(0)
	s_barrier
	ds_read_b128 v[108:111], v84 offset:58880
	ds_read_b32 v58, v75 offset:58112
	s_waitcnt lgkmcnt(1)
	v_mfma_f32_16x16x32_bf16 v[108:111], v[54:57], v[108:111], 0
	ds_read_b128 v[112:115], v84 offset:58944
	ds_read_b128 v[116:119], v84 offset:59008
	s_waitcnt lgkmcnt(2)
	v_cmp_gt_i32_e32 vcc, 0, v58
	s_waitcnt lgkmcnt(1)
	v_mfma_f32_16x16x32_bf16 v[108:111], v[46:49], v[112:115], v[108:111]
	s_waitcnt lgkmcnt(0)
	v_mfma_f32_16x16x32_bf16 v[108:111], v[50:53], v[116:119], v[108:111]
	ds_read_b128 v[112:115], v84 offset:59072
	ds_read_b128 v[116:119], v84 offset:59136
	s_waitcnt lgkmcnt(1)
	v_mfma_f32_16x16x32_bf16 v[108:111], v[42:45], v[112:115], v[108:111]
	s_waitcnt lgkmcnt(0)
	v_mfma_f32_16x16x32_bf16 v[108:111], v[22:25], v[116:119], v[108:111]
	ds_read_b128 v[112:115], v84 offset:59200
	ds_read_b128 v[116:119], v84 offset:59264
	s_waitcnt lgkmcnt(1)
	v_mfma_f32_16x16x32_bf16 v[108:111], v[18:21], v[112:115], v[108:111]
	ds_read_b128 v[112:115], v84 offset:59328
	s_waitcnt lgkmcnt(1)
	v_mfma_f32_16x16x32_bf16 v[108:111], v[14:17], v[116:119], v[108:111]
	s_waitcnt lgkmcnt(0)
	v_mfma_f32_16x16x32_bf16 v[108:111], v[10:13], v[112:115], v[108:111]
	s_nop 7
	v_mul_f32_e32 v67, 0x3db504f3, v108
	v_mul_f32_e32 v108, 0x3db504f3, v109
	v_mul_f32_e32 v109, 0x3db504f3, v110
	v_mul_f32_e32 v110, 0x3db504f3, v111
	v_cndmask_b32_e32 v58, v67, v72, vcc
	v_cndmask_b32_e32 v67, v108, v72, vcc
	v_cndmask_b32_e32 v108, v109, v72, vcc
	v_cndmask_b32_e32 v109, v110, v72, vcc
	ds_write2st64_b32 v76, v58, v67 offset0:66 offset1:70
	ds_write2st64_b32 v76, v108, v109 offset0:74 offset1:78
	s_waitcnt lgkmcnt(0)
	s_barrier
	s_waitcnt vmcnt(7)
	ds_write_b128 v73, v[26:29] offset:58880
	s_waitcnt vmcnt(6)
	ds_write_b128 v74, v[30:33] offset:8448
	s_waitcnt vmcnt(5)
	ds_write_b128 v74, v[34:37] offset:16896
	s_waitcnt vmcnt(4)
	ds_write_b128 v74, v[38:41] offset:25344
	s_waitcnt vmcnt(3)
	ds_write_b128 v77, v[92:95]
	s_waitcnt vmcnt(2)
	ds_write_b128 v77, v[96:99] offset:8448
	s_waitcnt vmcnt(1)
	ds_write_b128 v77, v[100:103] offset:16896
	s_waitcnt vmcnt(0)
	ds_write_b128 v77, v[104:107] offset:25344
	ds_read2_b32 v[26:27], v91 offset0:64 offset1:72
	ds_read2_b32 v[28:29], v91 offset0:80 offset1:88
	ds_read2_b32 v[34:35], v91 offset0:96 offset1:104
	ds_read2_b32 v[92:93], v91 offset0:112 offset1:120
	s_waitcnt lgkmcnt(3)
	v_max_i32_e32 v58, 0, v26
	v_lshlrev_b64 v[30:31], 10, v[58:59]
	v_max_i32_e32 v58, 0, v27
	v_lshlrev_b64 v[26:27], 10, v[58:59]
	s_waitcnt lgkmcnt(2)
	v_max_i32_e32 v58, 0, v28
	v_lshl_add_u64 v[36:37], v[62:63], 0, v[30:31]
	v_lshlrev_b64 v[40:41], 10, v[58:59]
	v_max_i32_e32 v58, 0, v29
	v_lshl_add_u64 v[38:39], v[62:63], 0, v[26:27]
	global_load_dwordx4 v[26:29], v[36:37], off
	global_load_dwordx4 v[30:33], v[38:39], off
	v_lshlrev_b64 v[36:37], 10, v[58:59]
	s_waitcnt lgkmcnt(1)
	v_max_i32_e32 v58, 0, v34
	v_lshl_add_u64 v[94:95], v[62:63], 0, v[40:41]
	v_lshlrev_b64 v[98:99], 10, v[58:59]
	v_max_i32_e32 v58, 0, v35
	v_lshl_add_u64 v[96:97], v[62:63], 0, v[36:37]
	global_load_dwordx4 v[34:37], v[94:95], off
	global_load_dwordx4 v[38:41], v[96:97], off
	v_lshlrev_b64 v[94:95], 10, v[58:59]
	s_waitcnt lgkmcnt(0)
	v_max_i32_e32 v58, 0, v92
	v_lshl_add_u64 v[100:101], v[62:63], 0, v[98:99]
	v_lshlrev_b64 v[104:105], 10, v[58:59]
	v_max_i32_e32 v58, 0, v93
	v_lshl_add_u64 v[102:103], v[62:63], 0, v[94:95]
	global_load_dwordx4 v[92:95], v[100:101], off
	global_load_dwordx4 v[96:99], v[102:103], off
	v_lshl_add_u64 v[108:109], v[62:63], 0, v[104:105]
	v_lshlrev_b64 v[100:101], 10, v[58:59]
	v_lshl_add_u64 v[110:111], v[62:63], 0, v[100:101]
	global_load_dwordx4 v[100:103], v[108:109], off
	global_load_dwordx4 v[104:107], v[110:111], off
	s_waitcnt lgkmcnt(0)
	s_barrier
	ds_read_b128 v[108:111], v85
	ds_read_b128 v[112:115], v85 offset:64
	s_waitcnt lgkmcnt(1)
	v_mfma_f32_16x16x32_bf16 v[108:111], v[54:57], v[108:111], 0
	s_waitcnt lgkmcnt(0)
	v_mfma_f32_16x16x32_bf16 v[108:111], v[46:49], v[112:115], v[108:111]
	ds_read_b128 v[112:115], v85 offset:128
	ds_read_b128 v[116:119], v85 offset:192
	s_waitcnt lgkmcnt(1)
	v_mfma_f32_16x16x32_bf16 v[108:111], v[50:53], v[112:115], v[108:111]
	s_waitcnt lgkmcnt(0)
	v_mfma_f32_16x16x32_bf16 v[108:111], v[42:45], v[116:119], v[108:111]
	ds_read_b128 v[112:115], v85 offset:256
	ds_read_b128 v[116:119], v85 offset:320
	s_waitcnt lgkmcnt(1)
	v_mfma_f32_16x16x32_bf16 v[108:111], v[22:25], v[112:115], v[108:111]
	s_waitcnt lgkmcnt(0)
	v_mfma_f32_16x16x32_bf16 v[108:111], v[18:21], v[116:119], v[108:111]
	ds_read_b128 v[112:115], v85 offset:384
	ds_read_b128 v[116:119], v85 offset:448
	ds_read_b32 v58, v75 offset:58368
	s_waitcnt lgkmcnt(0)
	v_cmp_gt_i32_e32 vcc, 0, v58
	v_mfma_f32_16x16x32_bf16 v[108:111], v[14:17], v[112:115], v[108:111]
	v_mfma_f32_16x16x32_bf16 v[108:111], v[10:13], v[116:119], v[108:111]
	s_nop 7
	v_mul_f32_e32 v67, 0x3db504f3, v108
	v_mul_f32_e32 v108, 0x3db504f3, v109
	v_mul_f32_e32 v109, 0x3db504f3, v110
	v_mul_f32_e32 v110, 0x3db504f3, v111
	v_cndmask_b32_e32 v58, v67, v72, vcc
	v_cndmask_b32_e32 v67, v108, v72, vcc
	v_cndmask_b32_e32 v108, v109, v72, vcc
	v_cndmask_b32_e32 v109, v110, v72, vcc
	ds_write2st64_b32 v76, v58, v67 offset0:67 offset1:71
	ds_write2st64_b32 v76, v108, v109 offset0:75 offset1:79
	s_waitcnt lgkmcnt(0)
	s_barrier
	s_waitcnt vmcnt(7)
	ds_write_b128 v73, v[26:29] offset:58880
	s_waitcnt vmcnt(6)
	ds_write_b128 v74, v[30:33] offset:8448
	s_waitcnt vmcnt(5)
	ds_write_b128 v74, v[34:37] offset:16896
	s_waitcnt vmcnt(4)
	ds_write_b128 v74, v[38:41] offset:25344
	s_waitcnt vmcnt(3)
	ds_write_b128 v74, v[92:95] offset:33792
	s_waitcnt vmcnt(2)
	ds_write_b128 v74, v[96:99] offset:42240
	s_waitcnt vmcnt(1)
	ds_write_b128 v74, v[100:103] offset:50688
	s_waitcnt vmcnt(0)
	ds_write_b128 v74, v[104:107] offset:59136
	ds_read2_b32 v[26:27], v91 offset1:8
	ds_read2_b32 v[28:29], v91 offset0:16 offset1:24
	s_waitcnt lgkmcnt(1)
	v_max_i32_e32 v58, 0, v26
	v_lshlrev_b64 v[30:31], 10, v[58:59]
	v_max_i32_e32 v58, 0, v27
	v_lshlrev_b64 v[26:27], 10, v[58:59]
	s_waitcnt lgkmcnt(0)
	v_max_i32_e32 v58, 0, v28
	v_lshl_add_u64 v[34:35], v[62:63], 0, v[30:31]
	v_lshlrev_b64 v[38:39], 10, v[58:59]
	v_max_i32_e32 v58, 0, v29
	v_lshl_add_u64 v[36:37], v[62:63], 0, v[26:27]
	global_load_dwordx4 v[26:29], v[34:35], off
	global_load_dwordx4 v[30:33], v[36:37], off
	v_lshl_add_u64 v[92:93], v[62:63], 0, v[38:39]
	v_lshlrev_b64 v[34:35], 10, v[58:59]
	v_lshl_add_u64 v[94:95], v[62:63], 0, v[34:35]
	global_load_dwordx4 v[34:37], v[92:93], off
	global_load_dwordx4 v[38:41], v[94:95], off
	s_waitcnt lgkmcnt(0)
	s_barrier
	ds_read_b128 v[92:95], v84 offset:58880
	ds_read_b32 v58, v75 offset:58624
	s_waitcnt lgkmcnt(1)
	v_mfma_f32_16x16x32_bf16 v[54:57], v[54:57], v[92:95], 0
	ds_read_b128 v[92:95], v84 offset:58944
	ds_read_b128 v[96:99], v84 offset:59008
	s_waitcnt lgkmcnt(2)
	v_cmp_gt_i32_e32 vcc, 0, v58
	s_waitcnt lgkmcnt(1)
	v_mfma_f32_16x16x32_bf16 v[46:49], v[46:49], v[92:95], v[54:57]
	s_waitcnt lgkmcnt(0)
	v_mfma_f32_16x16x32_bf16 v[46:49], v[50:53], v[96:99], v[46:49]
	ds_read_b128 v[50:53], v84 offset:59072
	ds_read_b128 v[54:57], v84 offset:59136
	s_waitcnt lgkmcnt(1)
	v_mfma_f32_16x16x32_bf16 v[42:45], v[42:45], v[50:53], v[46:49]
	v_mov_b32_e32 v50, v59
	v_mov_b32_e32 v51, v59
	s_nop 1
	ds_read_b128 v[46:49], v84 offset:59200
	s_waitcnt lgkmcnt(1)
	v_mfma_f32_16x16x32_bf16 v[22:25], v[22:25], v[54:57], v[42:45]
	v_mov_b32_e32 v52, v59
	s_nop 1
	ds_read_b128 v[42:45], v84 offset:59264
	s_waitcnt lgkmcnt(1)
	v_mfma_f32_16x16x32_bf16 v[18:21], v[18:21], v[46:49], v[22:25]
	v_mov_b32_e32 v47, v59
	v_mov_b32_e32 v46, v59
	s_nop 0
	ds_read_b128 v[22:25], v84 offset:59328
	s_waitcnt lgkmcnt(1)
	v_mfma_f32_16x16x32_bf16 v[14:17], v[14:17], v[42:45], v[18:21]
	v_mov_b32_e32 v42, v59
	v_mov_b32_e32 v43, v59
	v_mov_b32_e32 v44, v59
	s_waitcnt lgkmcnt(0)
	v_mfma_f32_16x16x32_bf16 v[10:13], v[10:13], v[22:25], v[14:17]
	s_nop 7
	v_mul_f32_e32 v10, 0x3db504f3, v10
	v_mul_f32_e32 v11, 0x3db504f3, v11
	v_mul_f32_e32 v12, 0x3db504f3, v12
	v_mul_f32_e32 v13, 0x3db504f3, v13
	v_cndmask_b32_e32 v10, v10, v72, vcc
	v_cndmask_b32_e32 v11, v11, v72, vcc
	v_cndmask_b32_e32 v12, v12, v72, vcc
	v_cndmask_b32_e32 v13, v13, v72, vcc
	ds_write2st64_b32 v76, v10, v11 offset0:68 offset1:72
	ds_write2st64_b32 v76, v12, v13 offset0:76 offset1:80
	s_waitcnt lgkmcnt(0)
	s_barrier
	ds_read2st64_b32 v[10:11], v78 offset0:65 offset1:66
	ds_read2st64_b32 v[12:13], v78 offset0:129 offset1:130
	ds_read2st64_b32 v[14:15], v78 offset0:131 offset1:132
	ds_read2st64_b32 v[16:17], v78 offset0:67 offset1:68
	ds_read2st64_b32 v[18:19], v79 offset0:65 offset1:66
	ds_read2st64_b32 v[20:21], v79 offset0:129 offset1:130
	ds_read2st64_b32 v[22:23], v79 offset0:131 offset1:132
	ds_read2st64_b32 v[24:25], v79 offset0:67 offset1:68
	s_waitcnt lgkmcnt(6)
	v_add_f32_e32 v10, v10, v12
	v_add_f32_e32 v11, v11, v13
	s_waitcnt lgkmcnt(4)
	v_add_f32_e32 v12, v16, v14
	v_add_f32_e32 v13, v17, v15
	s_waitcnt lgkmcnt(2)
	v_add_f32_e32 v14, v18, v20
	v_add_f32_e32 v15, v19, v21
	v_max3_f32 v18, v10, s17, v11
	s_waitcnt lgkmcnt(0)
	v_add_f32_e32 v16, v24, v22
	v_add_f32_e32 v17, v25, v23
	v_max3_f32 v19, v14, s17, v15
	v_max3_f32 v18, v18, v12, v13
	v_max3_f32 v19, v19, v16, v17
	s_nop 0
	v_mov_b32_dpp v50, v18 quad_perm:[1,0,3,2] row_mask:0xf bank_mask:0xf
	v_mov_b32_dpp v47, v19 quad_perm:[1,0,3,2] row_mask:0xf bank_mask:0xf
	v_max_f32_e32 v20, v50, v50
	v_max_f32_e32 v21, v47, v47
	v_max_f32_e32 v18, v18, v20
	v_max_f32_e32 v19, v19, v21
	s_nop 0
	v_mov_b32_dpp v51, v18 quad_perm:[2,3,0,1] row_mask:0xf bank_mask:0xf
	v_mov_b32_dpp v42, v19 quad_perm:[2,3,0,1] row_mask:0xf bank_mask:0xf
	v_max_f32_e32 v20, v51, v51
	v_max_f32_e32 v21, v42, v42
	v_max_f32_e32 v18, v18, v20
	v_max_f32_e32 v19, v19, v21
	s_nop 0
	v_mov_b32_dpp v52, v18 row_half_mirror row_mask:0xf bank_mask:0xf
	v_mov_b32_dpp v43, v19 row_half_mirror row_mask:0xf bank_mask:0xf
	v_max_f32_e32 v20, v52, v52
	v_max_f32_e32 v21, v43, v43
	v_max_f32_e32 v18, v18, v20
	v_max_f32_e32 v19, v19, v21
	s_nop 0
	v_mov_b32_dpp v46, v18 row_mirror row_mask:0xf bank_mask:0xf
	v_mov_b32_dpp v44, v19 row_mirror row_mask:0xf bank_mask:0xf
	v_max_f32_e32 v20, v46, v46
	v_max_f32_e32 v21, v44, v44
	v_max_f32_e32 v18, v18, v20
	v_max_f32_e32 v19, v19, v21
	v_readlane_b32 s11, v18, 32
	v_readlane_b32 s12, v18, 48
	v_readlane_b32 s7, v18, 0
	v_readlane_b32 s10, v18, 16
	v_readlane_b32 s13, v19, 0
	v_readlane_b32 s18, v19, 16
	v_readlane_b32 s19, v19, 32
	v_readlane_b32 s20, v19, 48
	v_max_f32_e64 v18, s12, s12
	v_max_f32_e64 v19, s11, s11
	v_mov_b32_e32 v20, s10
	v_max_f32_e64 v21, s20, s20
	v_max_f32_e64 v22, s19, s19
	v_max_f32_e32 v18, v19, v18
	v_mov_b32_e32 v23, s18
	v_max_f32_e32 v19, v22, v21
	v_max3_f32 v18, s7, v20, v18
	v_max3_f32 v19, s13, v23, v19
	v_sub_f32_e32 v10, v10, v18
	v_sub_f32_e32 v11, v11, v18
	v_sub_f32_e32 v14, v14, v19
	v_mul_f32_e32 v10, 0x3fb8aa3b, v10
	v_sub_f32_e32 v12, v12, v18
	v_sub_f32_e32 v15, v15, v19
	v_mul_f32_e32 v11, 0x3fb8aa3b, v11
	v_mul_f32_e32 v14, 0x3fb8aa3b, v14
	v_exp_f32_e32 v10, v10
	v_sub_f32_e32 v13, v13, v18
	v_sub_f32_e32 v16, v16, v19
	v_mul_f32_e32 v12, 0x3fb8aa3b, v12
	v_mul_f32_e32 v15, 0x3fb8aa3b, v15
	v_exp_f32_e32 v11, v11
	v_exp_f32_e32 v14, v14
	v_sub_f32_e32 v17, v17, v19
	v_mul_f32_e32 v13, 0x3fb8aa3b, v13
	v_mul_f32_e32 v16, 0x3fb8aa3b, v16
	v_exp_f32_e32 v12, v12
	v_exp_f32_e32 v15, v15
	v_mul_f32_e32 v17, 0x3fb8aa3b, v17
	v_exp_f32_e32 v13, v13
	v_exp_f32_e32 v16, v16
	v_exp_f32_e32 v17, v17
	v_add_f32_e32 v18, 0, v10
	v_add_f32_e32 v19, 0, v14
	v_add_f32_e32 v18, v11, v18
	v_add_f32_e32 v19, v15, v19
	v_add_f32_e32 v18, v12, v18
	v_add_f32_e32 v19, v16, v19
	v_add_f32_e32 v18, v13, v18
	v_add_f32_e32 v19, v17, v19
	s_nop 0
	v_add_f32_dpp v18, v18, v18 quad_perm:[1,0,3,2] row_mask:0xf bank_mask:0xf bound_ctrl:1
	v_add_f32_dpp v19, v19, v19 quad_perm:[1,0,3,2] row_mask:0xf bank_mask:0xf bound_ctrl:1
	s_nop 0
	v_add_f32_dpp v18, v18, v18 quad_perm:[2,3,0,1] row_mask:0xf bank_mask:0xf bound_ctrl:1
	v_add_f32_dpp v19, v19, v19 quad_perm:[2,3,0,1] row_mask:0xf bank_mask:0xf bound_ctrl:1
	s_nop 0
	v_add_f32_dpp v18, v18, v18 row_half_mirror row_mask:0xf bank_mask:0xf bound_ctrl:1
	v_add_f32_dpp v19, v19, v19 row_half_mirror row_mask:0xf bank_mask:0xf bound_ctrl:1
	s_nop 0
	v_add_f32_dpp v18, v18, v18 row_mirror row_mask:0xf bank_mask:0xf bound_ctrl:1
	v_add_f32_dpp v19, v19, v19 row_mirror row_mask:0xf bank_mask:0xf bound_ctrl:1
	v_readlane_b32 s10, v18, 16
	v_readlane_b32 s12, v18, 48
	v_readlane_b32 s7, v18, 0
	v_readlane_b32 s11, v18, 32
	v_readlane_b32 s13, v19, 0
	v_readlane_b32 s18, v19, 16
	v_readlane_b32 s19, v19, 32
	v_readlane_b32 s20, v19, 48
	v_mov_b32_e32 v18, s10
	v_mov_b32_e32 v19, s12
	v_add_f32_e32 v18, s7, v18
	v_add_f32_e32 v19, s11, v19
	v_add_f32_e32 v18, v18, v19
	v_div_scale_f32 v19, s[10:11], v18, v18, 1.0
	v_rcp_f32_e32 v22, v19
	v_div_scale_f32 v23, vcc, 1.0, v18, 1.0
	v_mov_b32_e32 v20, s18
	v_fma_f32 v24, -v19, v22, 1.0
	v_fmac_f32_e32 v22, v24, v22
	v_mul_f32_e32 v24, v23, v22
	v_fma_f32 v25, -v19, v24, v23
	v_fmac_f32_e32 v24, v25, v22
	v_fma_f32 v19, -v19, v24, v23
	v_div_fmas_f32 v19, v19, v22, v24
	v_div_fixup_f32 v18, v19, v18, 1.0
	v_mul_f32_e32 v10, v10, v18
	v_mul_f32_e32 v11, v11, v18
	v_mul_f32_e32 v12, v12, v18
	v_mul_f32_e32 v13, v13, v18
	v_bfe_u32 v18, v10, 16, 1
	v_mov_b32_e32 v21, s20
	v_bfe_u32 v19, v11, 16, 1
	v_bfe_u32 v22, v12, 16, 1
	v_add3_u32 v10, v10, v18, s9
	v_add_f32_e32 v20, s13, v20
	v_add3_u32 v11, v11, v19, s9
	v_add3_u32 v12, v12, v22, s9
	ds_write_b16_d16_hi v86, v10 offset:49408
	ds_write_b16_d16_hi v86, v11 offset:49536
	ds_write_b16_d16_hi v86, v12 offset:49664
	v_add_f32_e32 v10, s19, v21
	v_add_f32_e32 v10, v20, v10
	v_div_scale_f32 v11, s[10:11], v10, v10, 1.0
	v_rcp_f32_e32 v12, v11
	v_bfe_u32 v18, v13, 16, 1
	v_add3_u32 v13, v13, v18, s9
	ds_write_b16_d16_hi v86, v13 offset:49792
	v_fma_f32 v13, -v11, v12, 1.0
	v_fmac_f32_e32 v12, v13, v12
	v_div_scale_f32 v13, vcc, 1.0, v10, 1.0
	v_mul_f32_e32 v18, v13, v12
	v_fma_f32 v19, -v11, v18, v13
	v_fmac_f32_e32 v18, v19, v12
	v_fma_f32 v11, -v11, v18, v13
	v_div_fmas_f32 v11, v11, v12, v18
	v_div_fixup_f32 v10, v11, v10, 1.0
	v_mul_f32_e32 v11, v14, v10
	v_bfe_u32 v12, v11, 16, 1
	v_add3_u32 v11, v11, v12, s9
	ds_write_b16_d16_hi v87, v11 offset:49408
	v_mul_f32_e32 v11, v15, v10
	v_bfe_u32 v12, v11, 16, 1
	v_add3_u32 v11, v11, v12, s9
	ds_write_b16_d16_hi v87, v11 offset:49536
	v_mul_f32_e32 v11, v16, v10
	v_bfe_u32 v12, v11, 16, 1
	v_add3_u32 v11, v11, v12, s9
	v_mul_f32_e32 v10, v17, v10
	ds_write_b16_d16_hi v87, v11 offset:49664
	v_bfe_u32 v11, v10, 16, 1
	s_cselect_b64 s[10:11], -1, 0
	v_add3_u32 v10, v10, v11, s9
	s_and_b64 vcc, exec, s[10:11]
	ds_write_b16_d16_hi v87, v10 offset:49792
	s_cbranch_vccnz .LBB0_1399
	s_ashr_i32 s7, s6, 31
	s_lshl_b64 s[12:13], s[6:7], 14
	s_add_u32 s12, s14, s12
	s_addc_u32 s13, s15, s13
	v_mov_b32_e32 v67, v59
	v_lshl_add_u64 v[2:3], s[12:13], 0, v[66:67]
	v_add_co_u32_e32 v10, vcc, 0x2000, v2
	s_nop 1
	v_addc_co_u32_e32 v11, vcc, 0, v3, vcc
	global_load_dwordx4 v[2:5], v66, s[12:13]
	global_load_dwordx4 v[6:9], v[10:11], off
	s_and_saveexec_b64 s[12:13], s[4:5]
	s_cbranch_execz .LBB0_1398
	s_lshl_b64 s[18:19], s[6:7], 10
	v_lshl_add_u64 v[10:11], v[60:61], 0, s[18:19]
	global_load_dword v1, v[10:11], off
	s_branch .LBB0_1398
.LBB0_1405:
	s_waitcnt vmcnt(0)
	s_cmp_lt_u32 s93, 11
	s_cbranch_scc1 .LBB0_1459
	s_waitcnt vmcnt(0)
	s_barrier
	s_mov_b64 s[0:1], exec
	v_readlane_b32 s4, v254, 37
	v_readlane_b32 s5, v254, 38
	s_and_b64 s[4:5], s[0:1], s[4:5]
	s_mov_b64 exec, s[4:5]
	s_cbranch_execz .LBB0_1458
	s_add_u32 s4, s66, 0x200
	s_addc_u32 s5, s67, 0
	s_add_i32 s3, 0, 0x27f20
	v_mov_b32_e32 v1, s3
	s_waitcnt vmcnt(0) expcnt(0) lgkmcnt(0)
	ds_read_b32 v3, v1
	s_add_i32 s3, 0, 0x27f24
	v_mov_b32_e32 v1, s3
	ds_read_b32 v1, v1
	s_waitcnt lgkmcnt(1)
	v_cmp_ne_u32_e32 vcc, 0, v3
	s_cbranch_vccnz .LBB0_1422
	v_readlane_b32 s10, v254, 2
	s_add_u32 s6, s66, 0x1000
	v_readlane_b32 s11, v254, 3
	s_addc_u32 s7, s67, 0
	s_load_dwordx2 s[14:15], s[10:11], 0x4
	s_add_u32 s8, s66, 0x1100
	s_addc_u32 s9, s67, 0
	s_add_u32 s10, s66, 0x1200
	s_addc_u32 s11, s67, 0
	s_add_u32 s12, s66, 0x1300
	s_waitcnt lgkmcnt(0)
	s_mul_i32 s3, s14, s84
	s_addc_u32 s13, s67, 0
	s_mul_i32 s3, s3, s15
	s_mov_b32 s20, 1
	v_mov_b32_e32 v17, 0
	s_branch .LBB0_1410
